# norm_mod1 (layer-1 norm) prompt loop software-pipelined: next iteration's two bf16 rows loaded into spare registers during the current pair's normalise/store; counted waits recomputed (on top of the t
# speedup vs baseline: 1.0073x; 1.0073x over previous
; DI void phase_norm_mod(const Params& p, const Sub& s, int layer, bool from_out, bf16_t* dst) {
;   const int lane = VTID & 63, wave = VTID >> 6;
;   const float* mod = (const float*)(p.ws + W_MOD);
;   const float* gv = p.norm_g + layer * D;
;   const int stride = s.vg * 4, rhi = s.samp ? M : MP;
;   for (int r = (s.samp ? MP : 0) + s.vb * 4 + wave; r < rhi; r += 2 * stride) {
;     const int rr[2] = {r, (r + stride < rhi) ? r + stride : r};
;     const bool two = r + stride < rhi;
;     ...
;         const bf16_t* srcb = (const bf16_t*)p.out + (size_t)rr[q] * D;
; #pragma unroll
;         for (int i = 0; i < 4; ++i) ld_bf4(srcb + i * 256 + lane * 4, v[q][i].x, v[q][i].y, v[q][i].z, v[q][i].w);
.LBB0_803:
	s_or_b64 exec, exec, s[6:7]
	s_mov_b32 s2, 0
	s_waitcnt lgkmcnt(0)
	v_mov_b32_e32 v0, v182
	s_barrier
	v_mov_b32_e32 v2, v182
	v_ashrrev_i32_e32 v1, 8, v0
	v_mov_b32_e32 v0, v182
	v_readlane_b32 s0, v251, 7
	v_lshrrev_b32_e32 v2, 6, v2
	s_mov_b32 s14, 0x10000
	v_add_lshl_u32 v1, v1, s0, 2
	v_and_or_b32 v48, v2, 3, v1
	v_cmp_gt_i32_e32 vcc, s14, v48
	s_and_saveexec_b64 s[0:1], vcc
	s_xor_b64 s[0:1], exec, s[0:1]
	s_cbranch_execz .LBB0_809
	s_ashr_i32 s3, s2, 31
	v_readlane_b32 s4, v251, 3
	v_readlane_b32 s5, v251, 4
	s_add_u32 s2, s4, s2
	s_addc_u32 s3, s5, s3
	s_load_dwordx4 s[8:11], s[2:3], 0xf0
	s_load_dwordx2 s[4:5], s[2:3], 0x40
	v_lshlrev_b32_e32 v1, 2, v0
	v_and_b32_e32 v2, 0xfc, v1
	v_mov_b32_e32 v51, 0
	v_lshlrev_b32_e32 v50, 2, v2
	s_waitcnt lgkmcnt(0)
	v_lshl_add_u64 v[4:5], s[4:5], 0, v[50:51]
	s_mov_b64 s[4:5], 0x1000
	v_mbcnt_hi_u32_b32 v1, -1, v183
	v_lshl_add_u64 v[52:53], v[4:5], 0, s[4:5]
	v_and_b32_e32 v4, 64, v1
	v_xor_b32_e32 v3, 16, v1
	v_add_u32_e32 v4, 64, v4
	v_cmp_lt_i32_e32 vcc, v3, v4
	s_add_u32 s2, s10, 0x1080000
	v_readlane_b32 s6, v251, 1
	v_cndmask_b32_e32 v3, v1, v3, vcc
	v_lshlrev_b32_e32 v90, 2, v3
	v_xor_b32_e32 v3, 32, v1
	v_cmp_lt_i32_e32 vcc, v3, v4
	s_addc_u32 s3, s11, 0
	v_readlane_b32 s7, v251, 2
	v_cndmask_b32_e32 v1, v1, v3, vcc
	s_lshl_b32 s12, s6, 4
	v_lshlrev_b32_e32 v50, 1, v2
	v_and_b32_e32 v0, 63, v0
	v_ashrrev_i32_e32 v49, 31, v48
	v_lshlrev_b32_e32 v91, 2, v1
	v_or_b32_e32 v4, 0x100, v2
	v_or_b32_e32 v6, 0x200, v2
	v_or_b32_e32 v8, 0x300, v2
	v_lshl_add_u64 v[54:55], s[8:9], 0, v[50:51]
	v_lshl_add_u64 v[10:11], s[10:11], 0, v[50:51]
	s_mov_b64 s[6:7], 0x1800000
	v_lshlrev_b32_e32 v50, 3, v0
	v_lshlrev_b64 v[0:1], 11, v[48:49]
	s_ashr_i32 s13, s12, 31
	v_lshl_add_u64 v[56:57], v[10:11], 0, s[6:7]
	v_lshl_add_u64 v[58:59], s[10:11], 0, v[0:1]
	s_lshl_b64 s[10:11], s[12:13], 11
	v_lshl_add_u64 v[60:61], s[8:9], 0, v[0:1]
	s_mov_b64 s[8:9], 0
	s_movk_i32 s13, 0x3000
	v_lshlrev_b32_e32 v62, 2, v2
	v_mov_b32_e32 v63, v51
	v_lshlrev_b32_e32 v64, 2, v4
	v_mov_b32_e32 v65, v51
	v_lshlrev_b32_e32 v66, 2, v6
	v_mov_b32_e32 v67, v51
	v_lshlrev_b32_e32 v68, 2, v8
	v_mov_b32_e32 v69, v51
	v_mov_b64_e32 v[70:71], s[2:3]
	v_mov_b32_e32 v49, 0x358637bd
	s_mov_b32 s15, 0x800000
	s_mov_b32 s16, 0x1800000
	s_mov_b32 s17, 0xffff
	v_lshl_add_u64 v[202:203], v[60:61], 0, v[50:51]
	v_add_u32_e32 v204, s25, v48
	v_ashrrev_i32_e32 v205, 31, v204
	v_lshlrev_b64 v[204:205], 11, v[204:205]
	v_lshl_add_u64 v[204:205], v[54:55], 0, v[204:205]
	global_load_dwordx2 v[208:209], v[202:203], off
	global_load_dwordx2 v[210:211], v[202:203], off offset:512
	global_load_dwordx2 v[212:213], v[202:203], off offset:1024
	global_load_dwordx2 v[214:215], v[202:203], off offset:1536
	global_load_dwordx2 v[216:217], v[204:205], off
	global_load_dwordx2 v[218:219], v[204:205], off offset:512
	global_load_dwordx2 v[220:221], v[204:205], off offset:1024
	global_load_dwordx2 v[222:223], v[204:205], off offset:1536
	s_waitcnt vmcnt(0)
	s_branch .LBB0_806

; DI float4 ldnt4(const float* p) { const f32x4 v = __builtin_nontemporal_load((const f32x4*)p); float4 r; r.x = v[0]; r.y = v[1]; r.z = v[2]; r.w = v[3]; return r; }
; DI void phase_norm_mod(const Params& p, const Sub& s, int layer, bool from_out, bf16_t* dst) {
;     ...
;   for (int r = (s.samp ? MP : 0) + s.vb * 4 + wave; r < rhi; r += 2 * stride) {
;     const int rr[2] = {r, (r + stride < rhi) ? r + stride : r};
;     const bool two = r + stride < rhi;
;     float4 v[2][4], g4[4], sh[2][4], sc[2][4];
; #pragma unroll
;     for (int q = 0; q < 2; ++q) {
;       if (from_out) {
;         const bf16_t* srcb = (const bf16_t*)p.out + (size_t)rr[q] * D;
; #pragma unroll
;         for (int i = 0; i < 4; ++i) ld_bf4(srcb + i * 256 + lane * 4, v[q][i].x, v[q][i].y, v[q][i].z, v[q][i].w);
;       } else {
;         const float* src = xrow(p, rr[q]);
; #pragma unroll
;         for (int i = 0; i < 4; ++i) v[q][i] = ldnt4(src + i * 256 + lane * 4);
;       }
;       const float* mrow = mod + (size_t)(row_bi(rr[q]) * 2 + layer) * 3072;
; #pragma unroll
;       for (int i = 0; i < 4; ++i) { const int c = i * 256 + lane * 4; sh[q][i] = *(const float4*)(mrow + c); sc[q][i] = *(const float4*)(mrow + 1024 + c); }
;     }
; #pragma unroll
;     for (int i = 0; i < 4; ++i) g4[i] = *(const float4*)(gv + i * 256 + lane * 4);
; #pragma unroll
;     for (int q = 0; q < 2; ++q) {
;       float ss = 0.f;
; #pragma unroll
;       for (int i = 0; i < 4; ++i) ss += v[q][i].x * v[q][i].x + v[q][i].y * v[q][i].y + v[q][i].z * v[q][i].z + v[q][i].w * v[q][i].w;
.LBB0_806:
	s_waitcnt vmcnt(8)
	v_add_u32_e32 v72, s25, v48
	v_cmp_gt_i32_e32 vcc, s14, v72
	v_lshl_add_u64 v[0:1], v[60:61], 0, v[50:51]
	v_mov_b64_e32 v[24:25], v[208:209]
	v_mov_b64_e32 v[26:27], v[210:211]
	v_mov_b64_e32 v[28:29], v[212:213]
	v_cndmask_b32_e32 v12, v48, v72, vcc
	v_ashrrev_i32_e32 v13, 31, v12
	v_mov_b64_e32 v[30:31], v[214:215]
	v_lshlrev_b64 v[0:1], 11, v[12:13]
	v_lshl_add_u64 v[0:1], v[54:55], 0, v[0:1]
	v_mov_b64_e32 v[36:37], v[216:217]
	v_mov_b64_e32 v[38:39], v[218:219]
	v_mov_b64_e32 v[40:41], v[220:221]
	v_mov_b64_e32 v[42:43], v[222:223]
	v_ashrrev_i32_e32 v13, 12, v48
	v_or_b32_e32 v13, 1, v13
	v_mul_hi_i32_i24_e32 v15, 0x3000, v13
	v_mul_i32_i24_e32 v14, 0x3000, v13
	v_lshl_add_u64 v[14:15], s[2:3], 0, v[14:15]
	v_lshl_add_u64 v[16:17], v[14:15], 0, s[4:5]
	v_lshl_add_u64 v[120:121], v[14:15], 0, v[62:63]
	global_load_dwordx4 v[8:11], v[52:53], off
	global_load_dwordx4 v[4:7], v[52:53], off offset:1024
	global_load_dwordx4 v[0:3], v[52:53], off offset:2048
	v_lshl_add_u64 v[14:15], v[16:17], 0, v[62:63]
	s_waitcnt lgkmcnt(0)
	global_load_dwordx4 v[92:95], v[120:121], off
	global_load_dwordx4 v[96:99], v[120:121], off offset:1024
	v_lshl_add_u64 v[18:19], v[16:17], 0, v[64:65]
	v_lshl_add_u64 v[20:21], v[16:17], 0, v[66:67]
	v_lshl_add_u64 v[16:17], v[16:17], 0, v[68:69]
	global_load_dwordx4 v[100:103], v[14:15], off
	global_load_dwordx4 v[104:107], v[18:19], off
	global_load_dwordx4 v[108:111], v[20:21], off
	global_load_dwordx4 v[112:115], v[16:17], off
	v_add_u32_e32 v13, 0xffff0000, v12
	v_lshrrev_b32_e32 v13, 4, v13
	v_ashrrev_i32_e32 v22, 13, v12
	v_add_u32_e32 v13, 8, v13
	v_cmp_gt_i32_e64 s[6:7], s14, v12
	s_nop 0
	v_lshlrev_b32_e32 v126, 16, v24
	v_cndmask_b32_e64 v12, v13, v22, s[6:7]
	v_lshl_or_b32 v12, v12, 1, 1
	v_mad_i64_i32 v[12:13], s[6:7], v12, s13, v[70:71]
	v_lshl_add_u64 v[14:15], v[12:13], 0, s[4:5]
	v_lshl_add_u64 v[44:45], v[12:13], 0, v[62:63]
	v_lshl_add_u64 v[46:47], v[14:15], 0, v[62:63]
	v_lshl_add_u64 v[74:75], v[14:15], 0, v[64:65]
	v_lshl_add_u64 v[122:123], v[14:15], 0, v[66:67]
	v_lshl_add_u64 v[124:125], v[14:15], 0, v[68:69]
	global_load_dwordx4 v[20:23], v[44:45], off
	global_load_dwordx4 v[12:15], v[44:45], off offset:1024
	global_load_dwordx4 v[32:35], v[46:47], off
	global_load_dwordx4 v[16:19], v[74:75], off
	v_and_b32_e32 v127, 0xffff0000, v24
	v_lshlrev_b32_e32 v128, 16, v25
	v_and_b32_e32 v129, 0xffff0000, v25
	s_nop 0
	v_lshlrev_b32_e32 v130, 16, v26
	v_and_b32_e32 v131, 0xffff0000, v26
	v_lshlrev_b32_e32 v132, 16, v27
	v_and_b32_e32 v133, 0xffff0000, v27
	s_nop 0
	v_lshlrev_b32_e32 v134, 16, v28
	v_and_b32_e32 v135, 0xffff0000, v28
	v_lshlrev_b32_e32 v136, 16, v29
	v_and_b32_e32 v137, 0xffff0000, v29
	s_nop 0
	v_lshlrev_b32_e32 v138, 16, v30
	v_and_b32_e32 v139, 0xffff0000, v30
	v_lshlrev_b32_e32 v140, 16, v31
	v_and_b32_e32 v141, 0xffff0000, v31
	s_nop 0
	v_lshlrev_b32_e32 v88, 16, v36
	v_and_b32_e32 v89, 0xffff0000, v36
	v_lshlrev_b32_e32 v86, 16, v37
	v_and_b32_e32 v87, 0xffff0000, v37
	s_nop 0
	v_lshlrev_b32_e32 v84, 16, v38
	v_and_b32_e32 v85, 0xffff0000, v38
	v_lshlrev_b32_e32 v82, 16, v39
	v_and_b32_e32 v83, 0xffff0000, v39
	global_load_dwordx4 v[116:119], v[120:121], off offset:2048
	global_load_dwordx4 v[36:39], v[44:45], off offset:2048
	global_load_dwordx4 v[24:27], v[44:45], off offset:3072
	global_load_dwordx4 v[28:31], v[52:53], off offset:3072
	v_mov_b32_e32 v46, v127
	v_mov_b32_e32 v47, v131
	v_mov_b32_e32 v44, v126
	v_mov_b32_e32 v45, v130
	v_pk_mul_f32 v[46:47], v[46:47], v[46:47]
	s_nop 0
	v_lshlrev_b32_e32 v80, 16, v40
	v_and_b32_e32 v81, 0xffff0000, v40
	v_lshlrev_b32_e32 v78, 16, v41
	v_and_b32_e32 v79, 0xffff0000, v41
	v_mov_b32_e32 v40, v128
	v_mov_b32_e32 v41, v132
	v_pk_fma_f32 v[44:45], v[44:45], v[44:45], v[46:47]
	v_mov_b32_e32 v142, v135
	v_mov_b32_e32 v143, v139
	s_nop 0
	v_lshlrev_b32_e32 v76, 16, v42
	v_and_b32_e32 v77, 0xffff0000, v42
	v_lshlrev_b32_e32 v74, 16, v43
	v_and_b32_e32 v75, 0xffff0000, v43
	v_mov_b32_e32 v42, v129
	v_mov_b32_e32 v43, v133
	v_pk_fma_f32 v[40:41], v[40:41], v[40:41], v[44:45]
	v_mov_b32_e32 v46, v134
	v_mov_b32_e32 v47, v138
	v_pk_mul_f32 v[142:143], v[142:143], v[142:143]
	v_pk_fma_f32 v[40:41], v[42:43], v[42:43], v[40:41]
	v_mov_b32_e32 v42, v136
	v_mov_b32_e32 v43, v140
	v_pk_fma_f32 v[46:47], v[46:47], v[46:47], v[142:143]
	v_mov_b32_e32 v44, v137
	v_mov_b32_e32 v45, v141
	v_pk_fma_f32 v[42:43], v[42:43], v[42:43], v[46:47]
	v_add_f32_e32 v40, v40, v41
	v_pk_fma_f32 v[42:43], v[44:45], v[44:45], v[42:43]
	s_waitcnt vmcnt(11)
	v_pk_add_f32 v[100:101], v[100:101], 1.0 op_sel_hi:[1,0]
	v_add_f32_e32 v40, v40, v42
	v_add_f32_e32 v40, v40, v43
	v_pk_add_f32 v[102:103], v[102:103], 1.0 op_sel_hi:[1,0]
	s_waitcnt vmcnt(10)
	v_pk_add_f32 v[104:105], v[104:105], 1.0 op_sel_hi:[1,0]
	v_add_f32_dpp v40, v40, v40 quad_perm:[1,0,3,2] row_mask:0xf bank_mask:0xf bound_ctrl:1
	v_pk_add_f32 v[106:107], v[106:107], 1.0 op_sel_hi:[1,0]
	s_waitcnt vmcnt(9)
	v_pk_add_f32 v[108:109], v[108:109], 1.0 op_sel_hi:[1,0]
	v_add_f32_dpp v40, v40, v40 quad_perm:[2,3,0,1] row_mask:0xf bank_mask:0xf bound_ctrl:1
	v_pk_add_f32 v[110:111], v[110:111], 1.0 op_sel_hi:[1,0]
	s_waitcnt vmcnt(8)
; DI void st_bf4(bf16_t* p, float a, float b, float c, float d) { uint2 v; v.x = pack2(a, b); v.y = pack2(c, d); *(uint2*)p = v; }
; DI void phase_norm_mod(const Params& p, const Sub& s, int layer, bool from_out, bf16_t* dst) {
;     ...
;         const bf16_t* srcb = (const bf16_t*)p.out + (size_t)rr[q] * D;
; #pragma unroll
;         for (int i = 0; i < 4; ++i) ld_bf4(srcb + i * 256 + lane * 4, v[q][i].x, v[q][i].y, v[q][i].z, v[q][i].w);
;     ...
;     for (int q = 0; q < 2; ++q) {
;       float ss = 0.f;
; #pragma unroll
;       for (int i = 0; i < 4; ++i) ss += v[q][i].x * v[q][i].x + v[q][i].y * v[q][i].y + v[q][i].z * v[q][i].z + v[q][i].w * v[q][i].w;
;       ss = wave_sum(ss);
;       const float rs = rsqrtf(ss * (1.0f / D) + EPS);
;       if (q == 0 || two) {
; #pragma unroll
;         for (int i = 0; i < 4; ++i) {
;           const int c = i * 256 + lane * 4;
;           st_bf4(dst + (size_t)rr[q] * D + c, v[q][i].x * rs * g4[i].x * (1.f + sc[q][i].x) + sh[q][i].x, v[q][i].y * rs * g4[i].y * (1.f + sc[q][i].y) + sh[q][i].y,
;                  v[q][i].z * rs * g4[i].z * (1.f + sc[q][i].z) + sh[q][i].z, v[q][i].w * rs * g4[i].w * (1.f + sc[q][i].w) + sh[q][i].w);
;         }
	v_pk_add_f32 v[112:113], v[112:113], 1.0 op_sel_hi:[1,0]
	v_add_f32_dpp v40, v40, v40 row_half_mirror row_mask:0xf bank_mask:0xf bound_ctrl:1
	s_nop 1
	v_add_f32_dpp v73, v40, v40 row_mirror row_mask:0xf bank_mask:0xf bound_ctrl:1
	global_load_dwordx4 v[44:47], v[122:123], off
	global_load_dwordx4 v[40:43], v[124:125], off
	s_nop 0
	global_load_dwordx4 v[120:123], v[120:121], off offset:3072
	v_add_u32_e32 v200, s12, v48
	v_cmp_ge_i32_e64 s[30:31], s17, v200
	s_and_saveexec_b64 s[34:35], s[30:31]
	v_lshl_add_u64 v[202:203], v[60:61], 0, v[50:51]
	v_lshl_add_u64 v[202:203], v[202:203], 0, s[10:11]
	v_add_u32_e32 v204, s25, v200
	v_ashrrev_i32_e32 v205, 31, v204
	v_lshlrev_b64 v[204:205], 11, v[204:205]
	v_lshl_add_u64 v[204:205], v[54:55], 0, v[204:205]
	global_load_dwordx2 v[208:209], v[202:203], off
	global_load_dwordx2 v[210:211], v[202:203], off offset:512
	global_load_dwordx2 v[212:213], v[202:203], off offset:1024
	global_load_dwordx2 v[214:215], v[202:203], off offset:1536
	global_load_dwordx2 v[216:217], v[204:205], off
	global_load_dwordx2 v[218:219], v[204:205], off offset:512
	global_load_dwordx2 v[220:221], v[204:205], off offset:1024
	global_load_dwordx2 v[222:223], v[204:205], off offset:1536
	s_or_b64 exec, exec, s[34:35]
	ds_bpermute_b32 v142, v90, v73
	v_lshl_add_u64 v[124:125], v[58:59], 0, v[50:51]
	s_waitcnt lgkmcnt(0)
	v_add_f32_e32 v73, v73, v142
	ds_bpermute_b32 v142, v91, v73
	s_waitcnt lgkmcnt(0)
	v_add_f32_e32 v73, v73, v142
	v_fmamk_f32 v73, v73, 0x3a800000, v49
	v_mul_f32_e32 v142, 0x4b800000, v73
	v_cmp_gt_f32_e64 s[6:7], s15, v73
	s_nop 1
	v_cndmask_b32_e64 v73, v73, v142, s[6:7]
	v_rsq_f32_e32 v73, v73
	s_nop 0
	v_mul_f32_e32 v142, 0x45800000, v73
	v_cndmask_b32_e64 v142, v73, v142, s[6:7]
	v_pk_mul_f32 v[126:127], v[142:143], v[126:127] op_sel_hi:[0,1]
	v_pk_mul_f32 v[126:127], v[8:9], v[126:127]
	s_nop 0
	v_pk_fma_f32 v[92:93], v[100:101], v[126:127], v[92:93]
	v_pk_mul_f32 v[100:101], v[142:143], v[128:129] op_sel_hi:[0,1]
	v_pk_mul_f32 v[100:101], v[10:11], v[100:101]
	v_cvt_pk_bf16_f32 v92, v92, v93
	v_pk_fma_f32 v[94:95], v[102:103], v[100:101], v[94:95]
	v_pk_mul_f32 v[100:101], v[84:85], v[84:85]
	v_cvt_pk_bf16_f32 v93, v94, v95
	v_add_co_u32_e64 v94, s[6:7], s16, v124
	v_pk_mul_f32 v[102:103], v[82:83], v[82:83]
	s_nop 0
	v_addc_co_u32_e64 v95, s[6:7], 0, v125, s[6:7]
	global_store_dwordx2 v[94:95], v[92:93], off
	v_pk_mul_f32 v[92:93], v[142:143], v[130:131] op_sel_hi:[0,1]
	v_pk_mul_f32 v[92:93], v[4:5], v[92:93]
	v_add_f32_e32 v73, v100, v101
	v_pk_fma_f32 v[92:93], v[104:105], v[92:93], v[96:97]
	v_pk_mul_f32 v[96:97], v[142:143], v[132:133] op_sel_hi:[0,1]
	v_pk_mul_f32 v[96:97], v[6:7], v[96:97]
	v_cvt_pk_bf16_f32 v92, v92, v93
	v_pk_fma_f32 v[96:97], v[106:107], v[96:97], v[98:99]
	v_pk_mul_f32 v[98:99], v[86:87], v[86:87]
	v_cvt_pk_bf16_f32 v93, v96, v97
	global_store_dwordx2 v[94:95], v[92:93], off offset:512
	v_pk_mul_f32 v[92:93], v[142:143], v[134:135] op_sel_hi:[0,1]
	v_pk_mul_f32 v[96:97], v[142:143], v[136:137] op_sel_hi:[0,1]
	v_pk_mul_f32 v[92:93], v[0:1], v[92:93]
	v_pk_mul_f32 v[96:97], v[2:3], v[96:97]
	s_waitcnt vmcnt(16)
	v_pk_fma_f32 v[92:93], v[108:109], v[92:93], v[116:117]
	v_pk_fma_f32 v[96:97], v[110:111], v[96:97], v[118:119]
	v_cvt_pk_bf16_f32 v92, v92, v93
	v_cvt_pk_bf16_f32 v93, v96, v97
	v_pk_mul_f32 v[96:97], v[88:89], v[88:89]
	v_add_f32_e32 v73, v73, v102
	v_add_f32_e32 v96, v96, v97
	v_add_f32_e32 v96, v96, v98
	v_pk_mul_f32 v[104:105], v[80:81], v[80:81]
	v_add_f32_e32 v73, v103, v73
	v_add_f32_e32 v96, v99, v96
	v_pk_mul_f32 v[106:107], v[78:79], v[78:79]
	v_add_f32_e32 v73, v96, v73
	v_add_f32_e32 v96, v104, v105
	v_add_f32_e32 v96, v96, v106
	v_pk_mul_f32 v[108:109], v[76:77], v[76:77]
	v_add_f32_e32 v96, v107, v96
	v_pk_mul_f32 v[110:111], v[74:75], v[74:75]
	v_add_f32_e32 v73, v73, v96
	v_add_f32_e32 v96, v108, v109
	v_add_f32_e32 v96, v96, v110
	v_add_f32_e32 v96, v111, v96
	v_add_f32_e32 v73, v73, v96
	global_store_dwordx2 v[94:95], v[92:93], off offset:1024
	v_pk_mul_f32 v[92:93], v[142:143], v[138:139] op_sel_hi:[0,1]
	v_add_f32_dpp v73, v73, v73 quad_perm:[1,0,3,2] row_mask:0xf bank_mask:0xf bound_ctrl:1
	s_waitcnt vmcnt(14)
	v_pk_mul_f32 v[92:93], v[28:29], v[92:93]
	v_pk_add_f32 v[100:101], v[114:115], 1.0 op_sel_hi:[1,0]
	v_add_f32_dpp v73, v73, v73 quad_perm:[2,3,0,1] row_mask:0xf bank_mask:0xf bound_ctrl:1
	s_waitcnt vmcnt(11)
	v_pk_fma_f32 v[96:97], v[112:113], v[92:93], v[120:121]
	v_pk_mul_f32 v[92:93], v[142:143], v[140:141] op_sel_hi:[0,1]
	v_add_f32_dpp v73, v73, v73 row_half_mirror row_mask:0xf bank_mask:0xf bound_ctrl:1
	v_pk_mul_f32 v[98:99], v[30:31], v[92:93]
	v_cvt_pk_bf16_f32 v96, v96, v97
	v_add_f32_dpp v73, v73, v73 row_mirror row_mask:0xf bank_mask:0xf bound_ctrl:1
	ds_bpermute_b32 v102, v90, v73
	v_pk_fma_f32 v[98:99], v[100:101], v[98:99], v[122:123]
	s_waitcnt lgkmcnt(0)
	v_add_f32_e32 v73, v73, v102
	ds_bpermute_b32 v92, v91, v73
	v_cvt_pk_bf16_f32 v97, v98, v99
	global_store_dwordx2 v[94:95], v[96:97], off offset:1536
	s_and_saveexec_b64 s[6:7], vcc
	s_cbranch_execz .LBB0_805
; DI void st_bf4(bf16_t* p, float a, float b, float c, float d) { uint2 v; v.x = pack2(a, b); v.y = pack2(c, d); *(uint2*)p = v; }
; DI void phase_norm_mod(const Params& p, const Sub& s, int layer, bool from_out, bf16_t* dst) {
;     ...
;       ss = wave_sum(ss);
;       const float rs = rsqrtf(ss * (1.0f / D) + EPS);
;       if (q == 0 || two) {
; #pragma unroll
;         for (int i = 0; i < 4; ++i) {
;           const int c = i * 256 + lane * 4;
;           st_bf4(dst + (size_t)rr[q] * D + c, v[q][i].x * rs * g4[i].x * (1.f + sc[q][i].x) + sh[q][i].x, v[q][i].y * rs * g4[i].y * (1.f + sc[q][i].y) + sh[q][i].y,
;                  v[q][i].z * rs * g4[i].z * (1.f + sc[q][i].z) + sh[q][i].z, v[q][i].w * rs * g4[i].w * (1.f + sc[q][i].w) + sh[q][i].w);
;         }
	s_waitcnt lgkmcnt(0)
	v_add_f32_e32 v73, v73, v92
	v_fmamk_f32 v73, v73, 0x3a800000, v49
	v_mul_f32_e32 v92, 0x4b800000, v73
	v_cmp_gt_f32_e32 vcc, s15, v73
	v_pk_add_f32 v[32:33], v[32:33], 1.0 op_sel_hi:[1,0]
	s_nop 0
	v_cndmask_b32_e32 v73, v73, v92, vcc
	v_rsq_f32_e32 v92, v73
	v_ashrrev_i32_e32 v73, 31, v72
	v_lshlrev_b64 v[72:73], 11, v[72:73]
	v_lshl_add_u64 v[72:73], v[56:57], 0, v[72:73]
	v_mul_f32_e32 v93, 0x45800000, v92
	v_cndmask_b32_e32 v92, v92, v93, vcc
	v_pk_mul_f32 v[88:89], v[92:93], v[88:89] op_sel_hi:[0,1]
	v_pk_mul_f32 v[8:9], v[8:9], v[88:89]
	s_nop 0
	v_pk_fma_f32 v[8:9], v[32:33], v[8:9], v[20:21]
	v_pk_mul_f32 v[32:33], v[92:93], v[86:87] op_sel_hi:[0,1]
	v_pk_add_f32 v[20:21], v[34:35], 1.0 op_sel_hi:[1,0]
	v_pk_mul_f32 v[10:11], v[10:11], v[32:33]
	v_cvt_pk_bf16_f32 v8, v8, v9
	v_pk_fma_f32 v[10:11], v[20:21], v[10:11], v[22:23]
	s_nop 0
	v_cvt_pk_bf16_f32 v9, v10, v11
	v_pk_mul_f32 v[10:11], v[92:93], v[84:85] op_sel_hi:[0,1]
	global_store_dwordx2 v[72:73], v[8:9], off
	v_pk_add_f32 v[8:9], v[16:17], 1.0 op_sel_hi:[1,0]
	v_pk_mul_f32 v[4:5], v[4:5], v[10:11]
	v_pk_mul_f32 v[10:11], v[92:93], v[82:83] op_sel_hi:[0,1]
	v_pk_fma_f32 v[4:5], v[8:9], v[4:5], v[12:13]
	v_pk_add_f32 v[8:9], v[18:19], 1.0 op_sel_hi:[1,0]
	v_pk_mul_f32 v[6:7], v[6:7], v[10:11]
	v_cvt_pk_bf16_f32 v4, v4, v5
	v_pk_fma_f32 v[6:7], v[8:9], v[6:7], v[14:15]
	s_nop 0
	v_cvt_pk_bf16_f32 v5, v6, v7
	v_pk_mul_f32 v[6:7], v[92:93], v[80:81] op_sel_hi:[0,1]
	global_store_dwordx2 v[72:73], v[4:5], off offset:512
	v_pk_add_f32 v[4:5], v[44:45], 1.0 op_sel_hi:[1,0]
	v_pk_mul_f32 v[0:1], v[0:1], v[6:7]
	v_pk_mul_f32 v[6:7], v[92:93], v[78:79] op_sel_hi:[0,1]
	v_pk_fma_f32 v[0:1], v[4:5], v[0:1], v[36:37]
	v_pk_add_f32 v[4:5], v[46:47], 1.0 op_sel_hi:[1,0]
	v_pk_mul_f32 v[2:3], v[2:3], v[6:7]
	v_cvt_pk_bf16_f32 v0, v0, v1
	v_pk_fma_f32 v[2:3], v[4:5], v[2:3], v[38:39]
	v_pk_mul_f32 v[4:5], v[92:93], v[74:75] op_sel_hi:[0,1]
	v_cvt_pk_bf16_f32 v1, v2, v3
	v_pk_mul_f32 v[2:3], v[92:93], v[76:77] op_sel_hi:[0,1]
	global_store_dwordx2 v[72:73], v[0:1], off offset:1024
	v_pk_add_f32 v[0:1], v[40:41], 1.0 op_sel_hi:[1,0]
	v_pk_mul_f32 v[2:3], v[28:29], v[2:3]
	v_pk_mul_f32 v[4:5], v[30:31], v[4:5]
	v_pk_fma_f32 v[0:1], v[0:1], v[2:3], v[24:25]
	v_pk_add_f32 v[2:3], v[42:43], 1.0 op_sel_hi:[1,0]
	v_cvt_pk_bf16_f32 v0, v0, v1
	v_pk_fma_f32 v[2:3], v[2:3], v[4:5], v[26:27]
	s_nop 0
	v_cvt_pk_bf16_f32 v1, v2, v3
	global_store_dwordx2 v[72:73], v[0:1], off offset:1536
	s_branch .LBB0_805
